# combo5 plus pipelined key-fragment LDS reads in cross-attention and neighbourhood-attention QK chains
# baseline (speedup 1.0000x reference)
.LBB0_432:
	s_cmp_ge_u32 s33, s25
	s_cselect_b64 s[0:1], -1, 0
	s_cmp_lt_u32 s33, s29
	s_cselect_b64 s[38:39], -1, 0
	s_and_b64 s[0:1], s[0:1], s[38:39]
	s_andn2_b64 vcc, exec, s[0:1]
	s_cbranch_vccnz .LBB0_438
	ds_read_b128 v[34:37], v166
	ds_read_b128 v[50:53], v166 offset:4096
	ds_read_b128 v[90:93], v167
	s_mov_b64 s[0:1], -1
	s_andn2_b64 vcc, exec, s[14:15]
	v_add_u32_e32 v177, s31, v132
	v_add_u32_e32 v176, s31, v133
	v_add_u32_e32 v175, s31, v134
	v_add_u32_e32 v174, s31, v135
	ds_read_b128 v[232:235], v167 offset:4096
	ds_read_b128 v[236:239], v168
	ds_read_b128 v[240:243], v168 offset:4096
	ds_read_b128 v[244:247], v169
	ds_read_b128 v[248:251], v169 offset:4096
	v_add_u32_e32 v173, s31, v144
	v_add_u32_e32 v172, s31, v146
	v_add_u32_e32 v171, s31, v148
	v_add_u32_e32 v170, s31, v150
	s_waitcnt lgkmcnt(7)
	v_mfma_f32_32x32x16_bf16 v[34:49], v[34:37], v[74:77], 0
	s_waitcnt lgkmcnt(6)
	v_mfma_f32_32x32x16_bf16 v[50:65], v[50:53], v[74:77], 0
	s_waitcnt lgkmcnt(5)
	v_mfma_f32_32x32x16_bf16 v[34:49], v[90:93], v[66:69], v[34:49]
	s_waitcnt lgkmcnt(4)
	v_mfma_f32_32x32x16_bf16 v[50:65], v[232:235], v[66:69], v[50:65]
	s_waitcnt lgkmcnt(3)
	v_mfma_f32_32x32x16_bf16 v[34:49], v[236:239], v[70:73], v[34:49]
	s_waitcnt lgkmcnt(2)
	v_mfma_f32_32x32x16_bf16 v[50:65], v[240:243], v[70:73], v[50:65]
	s_waitcnt lgkmcnt(1)
	v_mfma_f32_32x32x16_bf16 v[34:49], v[244:247], v[78:81], v[34:49]
	s_waitcnt lgkmcnt(0)
	v_mfma_f32_32x32x16_bf16 v[50:65], v[248:251], v[78:81], v[50:65]
	s_cbranch_vccnz .LBB0_435
	ds_read_b32 v212, v176 offset:25472
	ds_read_b32 v213, v177 offset:25472
	v_add_u32_e32 v214, s31, v151
	ds_read_b32 v214, v214 offset:25472
	ds_read_b32 v215, v175 offset:25472
	ds_read_b32 v216, v174 offset:25472
	v_add_u32_e32 v217, s31, v136
	ds_read_b32 v217, v217 offset:25472
	v_add_u32_e32 v218, s31, v137
	ds_read_b32 v218, v218 offset:25472
	v_add_u32_e32 v219, s31, v138
	ds_read_b32 v219, v219 offset:25472
	v_add_u32_e32 v220, s31, v139
	ds_read_b32 v220, v220 offset:25472
	v_add_u32_e32 v221, s31, v140
	ds_read_b32 v221, v221 offset:25472
	v_add_u32_e32 v222, s31, v141
	ds_read_b32 v222, v222 offset:25472
	v_add_u32_e32 v223, s31, v142
	ds_read_b32 v223, v223 offset:25472
	v_add_u32_e32 v224, s31, v143
	ds_read_b32 v224, v224 offset:25472
	ds_read_b32 v225, v173 offset:25472
	v_add_u32_e32 v226, s31, v145
	ds_read_b32 v226, v226 offset:25472
	ds_read_b32 v227, v172 offset:25472
	v_add_u32_e32 v228, s31, v147
	ds_read_b32 v228, v228 offset:25472
	ds_read_b32 v229, v171 offset:25472
	v_add_u32_e32 v230, s31, v149
	ds_read_b32 v230, v230 offset:25472
	ds_read_b32 v231, v170 offset:25472
	s_waitcnt lgkmcnt(0)
	v_mov_b32_e32 v91, v212
	v_add_u32_e32 v92, s31, v151
	v_mov_b32_e32 v90, v213
	s_mov_b64 s[0:1], 0
	v_mov_b32_e32 v92, v214
	s_waitcnt lgkmcnt(2)
	s_nop 4
	v_add_f32_e32 v91, v51, v91
	v_mul_f32_e32 v91, 0x3fb8aa3b, v91
	s_waitcnt lgkmcnt(0)
	v_add_f32_e32 v65, v65, v92
	v_exp_f32_e32 v99, v91
	v_mov_b32_e32 v91, v215
	v_mov_b32_e32 v92, 0
	v_mul_f32_e32 v65, 0x3fb8aa3b, v65
	s_waitcnt lgkmcnt(0)
	v_add_f32_e32 v91, v52, v91
	v_mul_f32_e32 v91, 0x3fb8aa3b, v91
	v_exp_f32_e32 v65, v65
	v_exp_f32_e32 v100, v91
	v_mov_b32_e32 v91, v216
	s_waitcnt lgkmcnt(0)
	v_add_f32_e32 v91, v53, v91
	v_mul_f32_e32 v91, 0x3fb8aa3b, v91
	s_nop 0
	v_exp_f32_e32 v101, v91
	v_add_u32_e32 v91, s31, v136
	v_mov_b32_e32 v91, v217
	s_waitcnt lgkmcnt(0)
	v_add_f32_e32 v54, v54, v91
	v_add_u32_e32 v91, s31, v137
	v_mov_b32_e32 v91, v218
	v_mul_f32_e32 v54, 0x3fb8aa3b, v54
	s_waitcnt lgkmcnt(0)
	v_add_f32_e32 v55, v55, v91
	v_add_u32_e32 v91, s31, v138
	v_mov_b32_e32 v91, v219
	v_exp_f32_e32 v54, v54
	v_mul_f32_e32 v55, 0x3fb8aa3b, v55
	s_waitcnt lgkmcnt(0)
	v_add_f32_e32 v56, v56, v91
	v_add_u32_e32 v91, s31, v139
	v_mov_b32_e32 v91, v220
	v_exp_f32_e32 v55, v55
	v_mul_f32_e32 v56, 0x3fb8aa3b, v56
	s_waitcnt lgkmcnt(0)
	v_add_f32_e32 v57, v57, v91
	v_mul_f32_e32 v57, 0x3fb8aa3b, v57
	v_exp_f32_e32 v56, v56
	v_exp_f32_e32 v102, v57
	v_add_u32_e32 v57, s31, v140
	v_mov_b32_e32 v57, v221
	s_waitcnt lgkmcnt(0)
	v_add_f32_e32 v57, v58, v57
	v_add_u32_e32 v58, s31, v141
	v_mov_b32_e32 v58, v222
	v_add_f32_e32 v90, v50, v90
	v_mul_f32_e32 v90, 0x3fb8aa3b, v90
	v_mul_f32_e32 v57, 0x3fb8aa3b, v57
	s_waitcnt lgkmcnt(0)
	v_add_f32_e32 v58, v59, v58
	v_add_u32_e32 v59, s31, v142
	v_mov_b32_e32 v59, v223
	v_exp_f32_e32 v98, v90
	v_mul_f32_e32 v58, 0x3fb8aa3b, v58
	v_exp_f32_e32 v57, v57
	s_waitcnt lgkmcnt(0)
	v_add_f32_e32 v59, v60, v59
	v_add_u32_e32 v60, s31, v143
	v_mov_b32_e32 v60, v224
	v_add_f32_e32 v90, 0, v98
	v_mul_f32_e32 v59, 0x3fb8aa3b, v59
	s_waitcnt lgkmcnt(0)
	v_add_f32_e32 v60, v61, v60
	v_mov_b32_e32 v61, v225
	v_add_f32_e32 v90, v90, v99
	v_exp_f32_e32 v58, v58
	v_add_f32_e32 v90, v90, v100
	s_waitcnt lgkmcnt(0)
	v_add_f32_e32 v61, v46, v61
	v_mul_f32_e32 v61, 0x3fb8aa3b, v61
	v_mul_f32_e32 v60, 0x3fb8aa3b, v60
	v_exp_f32_e32 v94, v61
	v_add_u32_e32 v61, s31, v145
	v_mov_b32_e32 v61, v226
	v_add_f32_e32 v90, v90, v101
	v_exp_f32_e32 v59, v59
	v_add_f32_e32 v90, v90, v54
	s_waitcnt lgkmcnt(0)
	v_add_f32_e32 v61, v62, v61
	v_mov_b32_e32 v62, v227
	v_mul_f32_e32 v61, 0x3fb8aa3b, v61
	v_add_f32_e32 v90, v90, v55
	s_waitcnt lgkmcnt(0)
	v_add_f32_e32 v62, v47, v62
	v_mul_f32_e32 v62, 0x3fb8aa3b, v62
	v_exp_f32_e32 v60, v60
	v_exp_f32_e32 v95, v62
	v_add_u32_e32 v62, s31, v147
	v_mov_b32_e32 v62, v228
	v_add_f32_e32 v90, v90, v56
	v_add_f32_e32 v91, 0, v94
	s_waitcnt lgkmcnt(0)
	v_add_f32_e32 v62, v63, v62
	v_mov_b32_e32 v63, v229
	v_add_f32_e32 v90, v90, v102
	v_exp_f32_e32 v61, v61
	v_add_f32_e32 v90, v90, v57
	s_waitcnt lgkmcnt(0)
	v_add_f32_e32 v63, v48, v63
	v_mul_f32_e32 v63, 0x3fb8aa3b, v63
	v_mul_f32_e32 v62, 0x3fb8aa3b, v62
	v_exp_f32_e32 v97, v63
	v_add_u32_e32 v63, s31, v149
	v_mov_b32_e32 v63, v230
	v_add_f32_e32 v90, v90, v58
	s_waitcnt lgkmcnt(0)
	v_add_f32_e32 v63, v64, v63
	v_mov_b32_e32 v64, v231
	v_add_f32_e32 v90, v90, v59
	v_exp_f32_e32 v62, v62
	v_add_f32_e32 v90, v90, v60
	v_mul_f32_e32 v63, 0x3fb8aa3b, v63
	s_waitcnt lgkmcnt(0)
	v_add_f32_e32 v64, v49, v64
	v_add_f32_e32 v90, v90, v61
	v_exp_f32_e32 v63, v63
	v_mul_f32_e32 v64, 0x3fb8aa3b, v64
	v_add_f32_e32 v90, v90, v62
	v_add_f32_e32 v91, v91, v95
	v_exp_f32_e32 v64, v64
	v_add_f32_e32 v90, v90, v63
	v_add_f32_e32 v91, v91, v97
	v_cvt_pk_bf16_f32 v96, v94, v95
	v_add_f32_e32 v90, v90, v65
	v_add_f32_e32 v91, v91, v64
	v_cvt_pk_bf16_f32 v97, v97, v64
	v_add_f32_e32 v90, v91, v90
	v_mov_b32_e32 v91, v90
	s_nop 1
	v_permlane32_swap_b32_e32 v90, v91
	v_add_f32_e32 v178, v90, v91
	v_mov_b32_e32 v90, 0
	s_nop 1
	v_permlane32_swap_b32_e32 v90, v92
	v_mov_b32_e32 v94, 0
	v_mov_b32_e32 v95, 0
	v_cvt_pk_bf16_f32 v98, v98, v99
	v_cvt_pk_bf16_f32 v99, v100, v101
	v_cvt_pk_bf16_f32 v100, v54, v55
	v_cvt_pk_bf16_f32 v101, v56, v102
	v_cvt_pk_bf16_f32 v102, v57, v58
	v_cvt_pk_bf16_f32 v103, v59, v60
	v_cvt_pk_bf16_f32 v104, v61, v62
	v_cvt_pk_bf16_f32 v105, v63, v65
	v_mov_b32_e32 v91, v90
	v_mov_b32_e32 v93, v92
	v_permlane32_swap_b32_e32 v94, v96
	v_permlane32_swap_b32_e32 v95, v97
	v_permlane32_swap_b32_e32 v98, v100
	v_permlane32_swap_b32_e32 v99, v101
	v_permlane32_swap_b32_e32 v102, v104
	v_permlane32_swap_b32_e32 v103, v105

.LBB0_946:
	ds_read_b128 v[66:69], v216
	ds_read_b128 v[232:235], v217
	ds_read_b128 v[236:239], v218
	ds_read_b128 v[240:243], v219
	ds_read_b128 v[244:247], v220
	ds_read_b128 v[248:251], v221
	s_andn2_b64 vcc, exec, s[16:17]
	s_mov_b64 s[14:15], s[0:1]
	s_waitcnt lgkmcnt(5)
	v_mfma_f32_32x32x16_bf16 v[66:81], v[66:69], v[82:85], 0
	s_waitcnt lgkmcnt(4)
	v_mfma_f32_32x32x16_bf16 v[66:81], v[232:235], v[86:89], v[66:81]
	ds_read_b128 v[232:235], v222
	s_waitcnt lgkmcnt(4)
	v_mfma_f32_32x32x16_bf16 v[66:81], v[236:239], v[90:93], v[66:81]
	ds_read_b128 v[236:239], v223
	s_waitcnt lgkmcnt(4)
	v_mfma_f32_32x32x16_bf16 v[66:81], v[240:243], v[94:97], v[66:81]
	ds_read_b128 v[240:243], v224
	s_waitcnt lgkmcnt(4)
	v_mfma_f32_32x32x16_bf16 v[66:81], v[244:247], v[98:101], v[66:81]
	ds_read_b128 v[244:247], v225
	s_waitcnt lgkmcnt(4)
	v_mfma_f32_32x32x16_bf16 v[66:81], v[248:251], v[102:105], v[66:81]
	ds_read_b128 v[248:251], v226
	s_waitcnt lgkmcnt(4)
	v_mfma_f32_32x32x16_bf16 v[66:81], v[232:235], v[106:109], v[66:81]
	ds_read_b128 v[232:235], v227
	s_waitcnt lgkmcnt(4)
	v_mfma_f32_32x32x16_bf16 v[66:81], v[236:239], v[110:113], v[66:81]
	ds_read_b128 v[236:239], v228
	s_waitcnt lgkmcnt(4)
	v_mfma_f32_32x32x16_bf16 v[66:81], v[240:243], v[114:117], v[66:81]
	ds_read_b128 v[240:243], v229
	s_waitcnt lgkmcnt(4)
	v_mfma_f32_32x32x16_bf16 v[66:81], v[244:247], v[118:121], v[66:81]
	ds_read_b128 v[244:247], v230
	s_waitcnt lgkmcnt(4)
	v_mfma_f32_32x32x16_bf16 v[66:81], v[248:251], v[122:125], v[66:81]
	ds_read_b128 v[248:251], v231
	s_waitcnt lgkmcnt(4)
	v_mfma_f32_32x32x16_bf16 v[66:81], v[232:235], v[126:129], v[66:81]
	s_waitcnt lgkmcnt(3)
	v_mfma_f32_32x32x16_bf16 v[66:81], v[236:239], v[130:133], v[66:81]
	s_waitcnt lgkmcnt(2)
	v_mfma_f32_32x32x16_bf16 v[66:81], v[240:243], v[134:137], v[66:81]
	s_waitcnt lgkmcnt(1)
	v_mfma_f32_32x32x16_bf16 v[66:81], v[244:247], v[138:141], v[66:81]
	s_waitcnt lgkmcnt(0)
	v_mfma_f32_32x32x16_bf16 v[66:81], v[248:251], v[142:145], v[66:81]
	s_nop 11
	v_mul_f32_e32 v66, 0x3fb8aa3b, v66
	v_mul_f32_e32 v67, 0x3fb8aa3b, v67
	v_exp_f32_e32 v66, v66
	v_mul_f32_e32 v68, 0x3fb8aa3b, v68
	v_mul_f32_e32 v70, 0x3fb8aa3b, v70
	v_exp_f32_e32 v67, v67
	v_mul_f32_e32 v69, 0x3fb8aa3b, v69
	v_exp_f32_e32 v68, v68
	v_exp_f32_e32 v178, v70
	v_add_f32_e32 v70, 0, v66
	v_mul_f32_e32 v71, 0x3fb8aa3b, v71
	v_exp_f32_e32 v69, v69
	v_add_f32_e32 v70, v67, v70
	v_mul_f32_e32 v72, 0x3fb8aa3b, v72
	v_add_f32_e32 v70, v68, v70
	v_exp_f32_e32 v202, v71
	v_add_f32_e32 v70, v69, v70
	v_mul_f32_e32 v73, 0x3fb8aa3b, v73
	v_exp_f32_e32 v203, v72
	v_add_f32_e32 v70, v178, v70
	v_mul_f32_e32 v74, 0x3fb8aa3b, v74
	v_exp_f32_e32 v73, v73
	v_add_f32_e32 v70, v202, v70
	v_mul_f32_e32 v75, 0x3fb8aa3b, v75
	v_exp_f32_e32 v206, v74
	v_add_f32_e32 v70, v203, v70
	v_mul_f32_e32 v76, 0x3fb8aa3b, v76
	v_exp_f32_e32 v207, v75
	v_add_f32_e32 v70, v73, v70
	v_mul_f32_e32 v77, 0x3fb8aa3b, v77
	v_exp_f32_e32 v76, v76
	v_add_f32_e32 v70, v206, v70
	v_mul_f32_e32 v78, 0x3fb8aa3b, v78
	v_exp_f32_e32 v77, v77
	v_add_f32_e32 v70, v207, v70
	v_mul_f32_e32 v79, 0x3fb8aa3b, v79
	v_exp_f32_e32 v78, v78
	v_add_f32_e32 v70, v76, v70
	v_mul_f32_e32 v80, 0x3fb8aa3b, v80
	v_exp_f32_e32 v79, v79
	v_add_f32_e32 v70, v77, v70
	v_mul_f32_e32 v81, 0x3fb8aa3b, v81
	v_exp_f32_e32 v80, v80
	v_add_f32_e32 v70, v78, v70
	v_cvt_pk_bf16_f32 v71, v68, v69
	v_exp_f32_e32 v81, v81
	v_add_f32_e32 v70, v79, v70
	v_cvt_pk_bf16_f32 v72, v178, v202
	v_add_f32_e32 v70, v80, v70
	v_cvt_pk_bf16_f32 v73, v203, v73
	v_add_f32_e32 v74, v81, v70
	v_cvt_pk_bf16_f32 v70, v66, v67
	s_nop 1
	v_permlane32_swap_b32_e32 v70, v72
	v_permlane32_swap_b32_e32 v71, v73
	v_cvt_pk_bf16_f32 v66, v206, v207
	v_cvt_pk_bf16_f32 v67, v76, v77
	v_cvt_pk_bf16_f32 v68, v78, v79
	v_cvt_pk_bf16_f32 v69, v80, v81
	v_add_u32_e32 v76, s13, v199
	v_permlane32_swap_b32_e32 v66, v68
	v_mov_b32_e32 v75, v74
	v_permlane32_swap_b32_e32 v67, v69
	ds_write_b128 v76, v[70:73]
	ds_write_b128 v76, v[66:69] offset:1024
	v_cndmask_b32_e64 v76, 0, 1, s[16:17]
	v_permlane32_swap_b32_e32 v74, v75
	v_cmp_ne_u32_e64 s[6:7], 1, v76
	s_waitcnt lgkmcnt(0)
	s_barrier
	s_cbranch_vccnz .LBB0_948
	v_mov_b32_e32 v76, v0
	s_andn2_b64 s[14:15], s[0:1], exec
	v_ashrrev_i32_e32 v77, 3, v76
	v_lshlrev_b32_e32 v76, 4, v76
	v_lshlrev_b32_e32 v78, 4, v77
	v_and_b32_e32 v76, 0x70, v76
	v_and_b32_e32 v78, 0xf0, v78
	v_lshl_add_u32 v77, v77, 9, 0
	v_xad_u32 v79, v78, v76, v77
	s_waitcnt vmcnt(7)
	ds_write_b128 v79, v[146:149]
	v_or_b32_e32 v79, 0x80, v76
	v_xad_u32 v79, v79, v78, v77
	s_waitcnt vmcnt(6)
	ds_write_b128 v79, v[150:153]
	v_or_b32_e32 v79, 0x100, v76
	v_or_b32_e32 v76, 0x180, v76
	v_xad_u32 v79, v79, v78, v77
	v_xad_u32 v76, v76, v78, v77
	s_waitcnt vmcnt(3)
	ds_write_b128 v79, v[162:165]
	s_waitcnt vmcnt(2)
	ds_write_b128 v76, v[166:169]
